# removed four conservative vmcnt(0) waits in GEMM prologues (INPROJ-L1, MLP1, MLP2-L1, ctx K-split) that drained the second prefetch batch
# baseline (speedup 1.0000x reference)
; #define PG8_STAGE(bufoff, gbase, voff) do { _Pragma("unroll") for (int _i = 0; _i < 2; ++_i) \
;         __builtin_amdgcn_global_load_lds((const unsigned*)((const char*)(gbase) + (voff)[_i]), (PG8_LAS unsigned*)(lds + (bufoff) + ldsw + _i * 8192), 16, 0, 0); } while (0)
; #define PG8_WAIT_V(n) asm volatile("s_waitcnt vmcnt(" #n ")" ::: "memory")
; #define PG8_BAR __builtin_amdgcn_s_barrier()
; template <class Epi, class Sched, bool ALIGN_EPI = false, bool SP2 = false>
; __device__ __forceinline__ void gemm_phase(PG8_LAS unsigned char* lds, const Gemm g, const Sched& S, const Epi& E) {
;     ...
;         PG8_STAGE(PG8_SB(0, 0), cB, voffB); PG8_STAGE(PG8_SB(0, 1), cB + hstep, voffB); PG8_STAGE(PG8_SA(0, 0), cA, voffA); PG8_STAGE(PG8_SA(0, 1), cA + hstep, voffA);
;         if (wr == 1) PG8_BAR;
;         PG8_WAIT_V(2); PG8_BAR;
;         PG8_STAGE(PG8_SB(1, 0), cB + kstep, voffB); PG8_STAGE(PG8_SA(1, 0), cA + kstep, voffA); PG8_STAGE(PG8_SB(1, 1), cB + hstep + kstep, voffB);
;         PG8_WAIT_V(6); PG8_BAR;
.LBB0_251:
	v_readlane_b32 s42, v255, 26
	s_lshl_b32 s8, s8, 5
	v_mov_b32_e32 v153, v187
	v_readlane_b32 s43, v255, 27
	s_and_b32 s11, s8, 0x60
	s_add_i32 m0, s31, 0x18000
	v_lshl_add_u64 v[0:1], v[0:1], 0, s[44:45]
	v_lshl_add_u64 v[12:13], s[42:43], 0, v[152:153]
	v_mov_b32_e32 v149, v187
	s_lshl_b32 s10, s7, 13
	s_lshl_b32 s36, s11, 7
	s_waitcnt vmcnt(2)
	s_barrier
	global_load_lds_dwordx4 v[0:1], off
	v_lshl_add_u64 v[0:1], v[2:3], 0, s[44:45]
	s_add_i32 m0, s31, 0x1a000
	s_add_i32 s49, s31, 0x8000
	s_add_i32 s52, s31, 0xa000
	v_lshl_add_u64 v[14:15], s[42:43], 0, v[148:149]
	global_load_lds_dwordx4 v[0:1], off
	v_lshl_add_u64 v[0:1], v[12:13], 0, s[44:45]
	s_mov_b32 m0, s49
	s_add_u32 s8, s12, 0x40080
	global_load_lds_dwordx4 v[0:1], off
	v_lshl_add_u64 v[0:1], v[14:15], 0, s[44:45]
	s_mov_b32 m0, s52
	s_addc_u32 s9, s13, 0
	global_load_lds_dwordx4 v[0:1], off
	s_add_i32 m0, s31, 0x1c000
	v_lshl_add_u64 v[0:1], s[8:9], 0, v[150:151]
	global_load_lds_dwordx4 v[0:1], off
	v_lshl_add_u64 v[0:1], s[8:9], 0, v[146:147]
	s_add_i32 m0, s31, 0x1e000
	s_movk_i32 s8, 0x700
	global_load_lds_dwordx4 v[0:1], off
	v_lshrrev_b32_e32 v1, 1, v6
	v_and_b32_e32 v1, 24, v1
	v_and_b32_e32 v0, 15, v6
	v_lshlrev_b32_e32 v2, 1, v1
	v_lshl_or_b32 v154, s7, 6, v0
	v_lshl_or_b32 v0, v0, 6, v2
	v_lshlrev_b32_e32 v2, 2, v6
	v_and_b32_e32 v2, 32, v2
	v_bitop3_b32 v3, v0, s10, v2 bitop3:0xde
	v_bitop3_b32 v145, v0, s36, v2 bitop3:0xde
	v_lshlrev_b32_e32 v0, 14, v9
	v_and_b32_e32 v0, 0xffff8000, v0
	v_or_b32_e32 v169, s11, v1
	v_lshl_add_u32 v0, v8, 11, v0
	v_and_b32_e32 v1, 1, v9
	v_lshl_or_b32 v0, v1, 6, v0
	v_lshl_add_u32 v164, v10, 1, v0
	v_lshlrev_b32_e32 v0, 14, v4
	v_and_b32_e32 v0, 0xffff8000, v0
	s_waitcnt vmcnt(6)
	v_lshl_add_u32 v0, v5, 11, v0
	v_and_b32_e32 v1, 1, v4
	s_cmpk_lt_u32 s6, 0x100
	v_mul_lo_u32 v168, v154, s8
	v_lshl_or_b32 v0, v1, 6, v0
	v_readlane_b32 s8, v255, 22
	s_cselect_b64 s[6:7], -1, 0
	v_mov_b32_e32 v155, v187
	v_add_u32_e32 v156, 0x80, v154
	v_mov_b32_e32 v157, v187
	v_add_u32_e32 v158, 0x90, v154
	v_mov_b32_e32 v159, v187
	v_add_u32_e32 v160, 0xa0, v154
	v_mov_b32_e32 v161, v187
	v_add_u32_e32 v162, 0xb0, v154
	v_mov_b32_e32 v163, v187
	v_mov_b32_e32 v165, v187
	v_lshl_add_u32 v166, v7, 1, v0
	v_mov_b32_e32 v167, v187
	s_mov_b32 s53, 0
	v_add_u32_e32 v170, 0, v3
	v_readlane_b32 s57, v255, 19
	s_mov_b32 s56, s8
	s_barrier
	v_readlane_b32 s9, v255, 23
	s_branch .LBB0_254

; #define PG8_STAGE(bufoff, gbase, voff) do { _Pragma("unroll") for (int _i = 0; _i < 2; ++_i) \
;         __builtin_amdgcn_global_load_lds((const unsigned*)((const char*)(gbase) + (voff)[_i]), (PG8_LAS unsigned*)(lds + (bufoff) + ldsw + _i * 8192), 16, 0, 0); } while (0)
; #define PG8_WAIT_V(n) asm volatile("s_waitcnt vmcnt(" #n ")" ::: "memory")
; #define PG8_BAR __builtin_amdgcn_s_barrier()
; template <class Epi, class Sched, bool ALIGN_EPI = false, bool SP2 = false>
; __device__ __forceinline__ void gemm_phase(PG8_LAS unsigned char* lds, const Gemm g, const Sched& S, const Epi& E) {
;     ...
;         PG8_STAGE(PG8_SB(0, 0), cB, voffB); PG8_STAGE(PG8_SB(0, 1), cB + hstep, voffB); PG8_STAGE(PG8_SA(0, 0), cA, voffA); PG8_STAGE(PG8_SA(0, 1), cA + hstep, voffA);
;         if (wr == 1) PG8_BAR;
;         PG8_WAIT_V(2); PG8_BAR;
;         PG8_STAGE(PG8_SB(1, 0), cB + kstep, voffB); PG8_STAGE(PG8_SA(1, 0), cA + kstep, voffA); PG8_STAGE(PG8_SB(1, 1), cB + hstep + kstep, voffB);
;         PG8_WAIT_V(6); PG8_BAR;
.LBB0_632:
	s_mul_i32 s7, s82, 0x24000
	v_readlane_b32 s8, v252, 36
	v_lshrrev_b32_e32 v16, 1, v14
	s_add_u32 s60, s8, s7
	v_readlane_b32 s7, v252, 37
	v_and_b32_e32 v16, 24, v16
	s_addc_u32 s61, s7, 0
	v_and_b32_e32 v15, 15, v14
	v_lshlrev_b32_e32 v17, 1, v16
	v_lshlrev_b32_e32 v14, 2, v14
	s_lshl_b32 s1, s1, 5
	v_lshl_or_b32 v154, s6, 6, v15
	v_lshl_or_b32 v15, v15, 6, v17
	s_lshl_b32 s6, s6, 13
	v_and_b32_e32 v14, 32, v14
	s_and_b32 s1, s1, 0x60
	s_add_i32 m0, s49, 0x18000
	v_lshl_add_u64 v[6:7], v[6:7], 0, s[44:45]
	v_bitop3_b32 v17, v15, s6, v14 bitop3:0xde
	s_lshl_b32 s6, s1, 7
	s_waitcnt vmcnt(2)
	s_barrier
	global_load_lds_dwordx4 v[6:7], off
	v_lshl_add_u64 v[4:5], v[4:5], 0, s[44:45]
	s_add_i32 m0, s49, 0x1a000
	s_add_i32 s64, s49, 0x8000
	s_add_i32 s65, s49, 0xa000
	v_bitop3_b32 v145, v15, s6, v14 bitop3:0xde
	global_load_lds_dwordx4 v[4:5], off
	v_lshl_add_u64 v[0:1], v[0:1], 0, s[44:45]
	s_mov_b32 m0, s64
	s_add_u32 s6, s12, 0x40080
	global_load_lds_dwordx4 v[0:1], off
	v_lshl_add_u64 v[0:1], v[2:3], 0, s[44:45]
	s_mov_b32 m0, s65
	s_addc_u32 s7, s13, 0
	global_load_lds_dwordx4 v[0:1], off
	s_add_i32 m0, s49, 0x1c000
	v_lshl_add_u64 v[0:1], s[6:7], 0, v[150:151]
	global_load_lds_dwordx4 v[0:1], off
	v_lshl_add_u64 v[0:1], s[6:7], 0, v[146:147]
	s_add_i32 m0, s49, 0x1e000
	s_cmpk_lt_u32 s0, 0x100
	global_load_lds_dwordx4 v[0:1], off
	v_lshlrev_b32_e32 v0, 14, v12
	v_and_b32_e32 v0, 0xffff8000, v0
	v_lshl_add_u32 v0, v11, 11, v0
	v_and_b32_e32 v1, 1, v12
	v_lshl_or_b32 v0, v1, 6, v0
	v_lshl_add_u32 v164, v13, 1, v0
	v_lshlrev_b32_e32 v0, 14, v8
	v_and_b32_e32 v0, 0xffff8000, v0
	s_waitcnt vmcnt(6)
	v_lshl_add_u32 v0, v9, 11, v0
	v_and_b32_e32 v1, 1, v8
	v_add_u32_e32 v156, 0x80, v154
	v_add_u32_e32 v158, 0x90, v154
	v_add_u32_e32 v160, 0xa0, v154
	v_add_u32_e32 v162, 0xb0, v154
	v_lshlrev_b32_e32 v168, 12, v154
	v_lshl_or_b32 v0, v1, 6, v0
	s_cselect_b64 s[6:7], -1, 0
	v_mov_b32_e32 v155, v187
	v_mov_b32_e32 v157, v187
	v_mov_b32_e32 v159, v187
	v_mov_b32_e32 v161, v187
	v_mov_b32_e32 v163, v187
	v_or_b32_e32 v169, 0x20000, v168
	v_or_b32_e32 v170, 0x30000, v168
	v_lshlrev_b32_e32 v171, 12, v156
	v_lshlrev_b32_e32 v172, 12, v158
	v_lshlrev_b32_e32 v173, 12, v160
	v_lshlrev_b32_e32 v174, 12, v162
	v_or_b32_e32 v175, s1, v16
	v_mov_b32_e32 v165, v187
	v_lshl_add_u32 v166, v10, 1, v0
	v_mov_b32_e32 v167, v187
	s_mov_b32 s66, 0
	v_add_u32_e32 v176, 0, v17
	s_barrier
	s_branch .LBB0_635

; #define PG8_STAGE(bufoff, gbase, voff) do { _Pragma("unroll") for (int _i = 0; _i < 2; ++_i) \
;         __builtin_amdgcn_global_load_lds((const unsigned*)((const char*)(gbase) + (voff)[_i]), (PG8_LAS unsigned*)(lds + (bufoff) + ldsw + _i * 8192), 16, 0, 0); } while (0)
; #define PG8_WAIT_V(n) asm volatile("s_waitcnt vmcnt(" #n ")" ::: "memory")
; #define PG8_BAR __builtin_amdgcn_s_barrier()
; template <class Epi, class Sched, bool ALIGN_EPI = false, bool SP2 = false>
; __device__ __forceinline__ void gemm_phase(PG8_LAS unsigned char* lds, const Gemm g, const Sched& S, const Epi& E) {
;     ...
;         PG8_STAGE(PG8_SB(0, 0), cB, voffB); PG8_STAGE(PG8_SB(0, 1), cB + hstep, voffB); PG8_STAGE(PG8_SA(0, 0), cA, voffA); PG8_STAGE(PG8_SA(0, 1), cA + hstep, voffA);
;         if (wr == 1) PG8_BAR;
;         PG8_WAIT_V(2); PG8_BAR;
;         PG8_STAGE(PG8_SB(1, 0), cB + kstep, voffB); PG8_STAGE(PG8_SA(1, 0), cA + kstep, voffA); PG8_STAGE(PG8_SB(1, 1), cB + hstep + kstep, voffB);
;         PG8_WAIT_V(6); PG8_BAR;
.LBB0_701:
	v_readlane_b32 s10, v255, 62
	v_and_b32_e32 v11, 15, v10
	v_lshrrev_b32_e32 v16, 1, v10
	s_lshl_b32 s6, s6, 5
	v_mov_b32_e32 v153, v187
	v_readlane_b32 s11, v255, 63
	v_and_b32_e32 v16, 24, v16
	v_lshlrev_b32_e32 v17, 6, v11
	v_lshlrev_b32_e32 v10, 2, v10
	s_and_b32 s8, s6, 0x60
	s_add_i32 m0, s35, 0x18000
	v_lshl_add_u64 v[0:1], v[0:1], 0, s[44:45]
	v_lshl_add_u64 v[12:13], s[10:11], 0, v[152:153]
	v_mov_b32_e32 v149, v187
	v_lshl_or_b32 v17, v16, 1, v17
	s_lshl_b32 s7, s0, 13
	v_and_b32_e32 v10, 32, v10
	s_lshl_b32 s6, s8, 7
	s_waitcnt vmcnt(2)
	s_barrier
	global_load_lds_dwordx4 v[0:1], off
	v_lshl_add_u64 v[0:1], v[2:3], 0, s[44:45]
	s_add_i32 m0, s35, 0x1a000
	s_add_i32 s53, s35, 0x8000
	s_add_i32 s54, s35, 0xa000
	v_lshl_add_u64 v[14:15], s[10:11], 0, v[148:149]
	v_bitop3_b32 v145, v17, s6, v10 bitop3:0xde
	global_load_lds_dwordx4 v[0:1], off
	v_lshl_add_u64 v[0:1], v[12:13], 0, s[44:45]
	s_mov_b32 m0, s53
	s_add_u32 s6, s12, 0x100080
	v_bitop3_b32 v18, v17, s7, v10 bitop3:0xde
	global_load_lds_dwordx4 v[0:1], off
	v_lshl_add_u64 v[0:1], v[14:15], 0, s[44:45]
	s_mov_b32 m0, s54
	s_addc_u32 s7, s13, 0
	global_load_lds_dwordx4 v[0:1], off
	s_add_i32 m0, s35, 0x1c000
	v_lshl_add_u64 v[0:1], s[6:7], 0, v[150:151]
	global_load_lds_dwordx4 v[0:1], off
	v_lshl_add_u64 v[0:1], s[6:7], 0, v[146:147]
	s_add_i32 m0, s35, 0x1e000
	s_cmpk_lt_u32 s1, 0x100
	global_load_lds_dwordx4 v[0:1], off
	v_lshlrev_b32_e32 v0, 10, v11
	v_lshl_or_b32 v155, s0, 16, v0
	v_lshlrev_b32_e32 v0, 16, v8
	v_and_b32_e32 v0, 0xfffe0000, v0
	v_lshl_add_u32 v0, v7, 13, v0
	v_and_b32_e32 v1, 1, v8
	v_lshl_or_b32 v0, v1, 6, v0
	v_lshl_add_u32 v156, v9, 1, v0
	v_lshlrev_b32_e32 v0, 16, v4
	v_and_b32_e32 v0, 0xfffe0000, v0
	v_readlane_b32 s0, v255, 57
	s_waitcnt vmcnt(6)
	v_lshl_add_u32 v0, v5, 13, v0
	v_and_b32_e32 v1, 1, v4
	v_readlane_b32 s1, v255, 58
	v_lshl_or_b32 v0, v1, 6, v0
	s_mov_b32 s56, s0
	v_readlane_b32 s0, v255, 55
	s_cselect_b64 s[6:7], -1, 0
	v_or_b32_e32 v154, s8, v16
	v_or_b32_e32 v160, 0x4000, v155
	v_or_b32_e32 v161, 0x8000, v155
	v_or_b32_e32 v162, 0xc000, v155
	s_mov_b32 s43, s77
	v_mov_b32_e32 v157, v187
	v_lshl_add_u32 v158, v6, 1, v0
	v_mov_b32_e32 v159, v187
	s_mov_b32 s55, 0
	v_add_u32_e32 v163, 0, v18
	s_mov_b32 s57, s0
	s_barrier
	v_readlane_b32 s1, v255, 56
	s_branch .LBB0_704

; #define PG8_STAGE(bufoff, gbase, voff) do { _Pragma("unroll") for (int _i = 0; _i < 2; ++_i) \
;         __builtin_amdgcn_global_load_lds((const unsigned*)((const char*)(gbase) + (voff)[_i]), (PG8_LAS unsigned*)(lds + (bufoff) + ldsw + _i * 8192), 16, 0, 0); } while (0)
; #define PG8_WAIT_V(n) asm volatile("s_waitcnt vmcnt(" #n ")" ::: "memory")
; #define PG8_BAR __builtin_amdgcn_s_barrier()
; template <class Epi, class Sched, bool ALIGN_EPI = false, bool SP2 = false>
; __device__ __forceinline__ void gemm_phase(PG8_LAS unsigned char* lds, const Gemm g, const Sched& S, const Epi& E) {
;     ...
;     f32x4 acc[2][2][4][2];
; #pragma unroll
;     for (int a = 0; a < 2; ++a)
; #pragma unroll
;         for (int b = 0; b < 2; ++b)
; #pragma unroll
;             for (int m = 0; m < 4; ++m)
; #pragma unroll
;                 for (int n = 0; n < 2; ++n) acc[a][b][m][n] = (f32x4){0.f, 0.f, 0.f, 0.f};
;     ...
;         PG8_STAGE(PG8_SB(0, 0), cB, voffB); PG8_STAGE(PG8_SB(0, 1), cB + hstep, voffB); PG8_STAGE(PG8_SA(0, 0), cA, voffA); PG8_STAGE(PG8_SA(0, 1), cA + hstep, voffA);
;         if (wr == 1) PG8_BAR;
;         PG8_WAIT_V(2); PG8_BAR;
;         PG8_STAGE(PG8_SB(1, 0), cB + kstep, voffB); PG8_STAGE(PG8_SA(1, 0), cA + kstep, voffA); PG8_STAGE(PG8_SB(1, 1), cB + hstep + kstep, voffB);
;         PG8_WAIT_V(6); PG8_BAR;
.LBB0_760:
	s_lshr_b32 s11, s29, 2
	s_and_b32 s12, s28, 3
	s_and_b32 s11, s11, 3
	s_lshl_b32 s12, s12, 11
	s_lshl_b32 s11, s11, 21
	s_or_b32 s11, s11, s12
	v_readlane_b32 s2, v253, 8
	s_add_u32 s41, s2, s11
	v_readlane_b32 s2, v253, 9
	s_addc_u32 s43, s2, 0
	v_and_b32_e32 v134, 15, v12
	s_lshl_b32 s10, s10, 5
	v_bfe_u32 v135, v12, 4, 2
	v_lshlrev_b32_e32 v15, 6, v134
	v_lshlrev_b32_e32 v12, 2, v12
	s_and_b32 s42, s10, 0x60
	s_add_i32 m0, s37, 0x18000
	v_lshl_add_u64 v[6:7], v[6:7], 0, s[44:45]
	v_lshl_or_b32 v15, v135, 4, v15
	s_lshl_b32 s11, s34, 13
	v_and_b32_e32 v12, 32, v12
	s_lshl_b32 s10, s42, 7
	s_waitcnt vmcnt(2)
	s_barrier
	global_load_lds_dwordx4 v[6:7], off
	v_lshl_add_u64 v[4:5], v[4:5], 0, s[44:45]
	s_add_i32 m0, s37, 0x1a000
	s_add_i32 s46, s37, 0x8000
	s_add_i32 s47, s37, 0xa000
	v_bitop3_b32 v136, v15, s10, v12 bitop3:0xde
	global_load_lds_dwordx4 v[4:5], off
	v_lshl_add_u64 v[2:3], v[2:3], 0, s[44:45]
	s_mov_b32 m0, s46
	s_add_u32 s10, s4, 0x100080
	v_bitop3_b32 v16, v15, s11, v12 bitop3:0xde
	global_load_lds_dwordx4 v[2:3], off
	v_lshl_add_u64 v[0:1], v[0:1], 0, s[44:45]
	s_mov_b32 m0, s47
	s_addc_u32 s11, s5, 0
	global_load_lds_dwordx4 v[0:1], off
	s_add_i32 m0, s37, 0x1c000
	v_lshl_add_u64 v[0:1], s[10:11], 0, v[186:187]
	global_load_lds_dwordx4 v[0:1], off
	v_lshl_add_u64 v[0:1], s[10:11], 0, v[128:129]
	s_add_i32 m0, s37, 0x1e000
	s_add_u32 s8, s8, s12
	global_load_lds_dwordx4 v[0:1], off
	s_addc_u32 s9, s9, 0
	v_lshlrev_b32_e32 v0, 16, v11
	s_add_u32 s48, s88, s8
	v_and_b32_e32 v0, 0xfffe0000, v0
	s_addc_u32 s49, s89, s9
	v_lshl_add_u32 v0, v13, 13, v0
	v_and_b32_e32 v1, 1, v11
	v_lshl_or_b32 v0, v1, 6, v0
	s_add_u32 s8, s83, s8
	v_lshl_add_u32 v0, v14, 1, v0
	v_mov_b32_e32 v1, v187
	s_addc_u32 s9, s93, s9
	v_lshl_add_u64 v[130:131], s[8:9], 0, v[0:1]
	v_lshlrev_b32_e32 v0, 16, v8
	v_and_b32_e32 v0, 0xfffe0000, v0
	v_lshl_add_u32 v0, v9, 13, v0
	v_and_b32_e32 v1, 1, v8
	v_lshl_or_b32 v0, v1, 6, v0
	s_waitcnt vmcnt(6)
	v_lshl_add_u32 v0, v10, 1, v0
	v_mov_b32_e32 v1, v187
	v_lshl_add_u64 v[132:133], s[8:9], 0, v[0:1]
	v_mov_b32_e32 v0, 0
	s_mov_b32 s52, -2
	s_mov_b64 s[8:9], 0
	v_add_u32_e32 v137, 0, v16
	v_mov_b32_e32 v1, v0
	v_mov_b32_e32 v2, v0
	v_mov_b32_e32 v3, v0
	v_mov_b32_e32 v4, v0
	v_mov_b32_e32 v5, v0
	v_mov_b32_e32 v6, v0
	v_mov_b32_e32 v7, v0
	v_mov_b32_e32 v8, v0
	v_mov_b32_e32 v9, v0
	v_mov_b32_e32 v10, v0
	v_mov_b32_e32 v11, v0
	v_mov_b32_e32 v12, v0
	v_mov_b32_e32 v13, v0
	v_mov_b32_e32 v14, v0
	v_mov_b32_e32 v15, v0
	v_mov_b32_e32 v16, v0
	v_mov_b32_e32 v17, v0
	v_mov_b32_e32 v18, v0
	v_mov_b32_e32 v19, v0
	v_mov_b32_e32 v20, v0
	v_mov_b32_e32 v21, v0
	v_mov_b32_e32 v22, v0
	v_mov_b32_e32 v23, v0
	v_mov_b32_e32 v28, v0
	v_mov_b32_e32 v29, v0
	v_mov_b32_e32 v30, v0
	v_mov_b32_e32 v31, v0
	v_mov_b32_e32 v36, v0
	v_mov_b32_e32 v37, v0
	v_mov_b32_e32 v38, v0
	v_mov_b32_e32 v39, v0
	v_mov_b32_e32 v24, v0
	v_mov_b32_e32 v25, v0
	v_mov_b32_e32 v26, v0
	v_mov_b32_e32 v27, v0
	v_mov_b32_e32 v32, v0
	v_mov_b32_e32 v33, v0
	v_mov_b32_e32 v34, v0
	v_mov_b32_e32 v35, v0
	v_mov_b32_e32 v40, v0
	v_mov_b32_e32 v41, v0
	v_mov_b32_e32 v42, v0
	v_mov_b32_e32 v43, v0
	v_mov_b32_e32 v44, v0
	v_mov_b32_e32 v45, v0
	v_mov_b32_e32 v46, v0
	v_mov_b32_e32 v47, v0
	v_mov_b32_e32 v48, v0
	v_mov_b32_e32 v49, v0
	v_mov_b32_e32 v50, v0
	v_mov_b32_e32 v51, v0
	v_mov_b32_e32 v52, v0
	v_mov_b32_e32 v53, v0
	v_mov_b32_e32 v54, v0
	v_mov_b32_e32 v55, v0
	v_mov_b32_e32 v56, v0
	v_mov_b32_e32 v57, v0
	v_mov_b32_e32 v58, v0
	v_mov_b32_e32 v59, v0
	v_mov_b32_e32 v60, v0
	v_mov_b32_e32 v61, v0
	v_mov_b32_e32 v62, v0
	v_mov_b32_e32 v63, v0
	v_mov_b32_e32 v64, v0
	v_mov_b32_e32 v65, v0
	v_mov_b32_e32 v66, v0
	v_mov_b32_e32 v67, v0
	v_mov_b32_e32 v68, v0
	v_mov_b32_e32 v69, v0
	v_mov_b32_e32 v70, v0
	v_mov_b32_e32 v71, v0
	v_mov_b32_e32 v72, v0
	v_mov_b32_e32 v73, v0
	v_mov_b32_e32 v74, v0
	v_mov_b32_e32 v75, v0
	v_mov_b32_e32 v76, v0
	v_mov_b32_e32 v77, v0
	v_mov_b32_e32 v78, v0
	v_mov_b32_e32 v79, v0
	v_mov_b32_e32 v80, v0
	v_mov_b32_e32 v81, v0
	v_mov_b32_e32 v82, v0
	v_mov_b32_e32 v83, v0
	v_mov_b32_e32 v88, v0
	v_mov_b32_e32 v89, v0
	v_mov_b32_e32 v90, v0
	v_mov_b32_e32 v91, v0
	v_mov_b32_e32 v96, v0
	v_mov_b32_e32 v97, v0
	v_mov_b32_e32 v98, v0
	v_mov_b32_e32 v99, v0
	v_mov_b32_e32 v104, v0
	v_mov_b32_e32 v105, v0
	v_mov_b32_e32 v106, v0
	v_mov_b32_e32 v107, v0
	v_mov_b32_e32 v84, v0
	v_mov_b32_e32 v85, v0
	v_mov_b32_e32 v86, v0
	v_mov_b32_e32 v87, v0
	v_mov_b32_e32 v92, v0
	v_mov_b32_e32 v93, v0
	v_mov_b32_e32 v94, v0
	v_mov_b32_e32 v95, v0
	v_mov_b32_e32 v100, v0
	v_mov_b32_e32 v101, v0
	v_mov_b32_e32 v102, v0
	v_mov_b32_e32 v103, v0
	v_mov_b32_e32 v108, v0
	v_mov_b32_e32 v109, v0
	v_mov_b32_e32 v110, v0
	v_mov_b32_e32 v111, v0
	v_mov_b32_e32 v112, v0
	v_mov_b32_e32 v113, v0
	v_mov_b32_e32 v114, v0
	v_mov_b32_e32 v115, v0
	v_mov_b32_e32 v116, v0
	v_mov_b32_e32 v117, v0
	v_mov_b32_e32 v118, v0
	v_mov_b32_e32 v119, v0
	v_mov_b32_e32 v120, v0
	v_mov_b32_e32 v121, v0
	v_mov_b32_e32 v122, v0
	v_mov_b32_e32 v123, v0
	v_mov_b32_e32 v124, v0
	v_mov_b32_e32 v125, v0
	v_mov_b32_e32 v126, v0
	v_mov_b32_e32 v127, v0
	s_barrier
; #define PG8_STAGE(bufoff, gbase, voff) do { _Pragma("unroll") for (int _i = 0; _i < 2; ++_i) \
;         __builtin_amdgcn_global_load_lds((const unsigned*)((const char*)(gbase) + (voff)[_i]), (PG8_LAS unsigned*)(lds + (bufoff) + ldsw + _i * 8192), 16, 0, 0); } while (0)
; #define PG8_LDA(dst, b, h) do { _Pragma("unroll") for (int m = 0; m < 4; ++m) _Pragma("unroll") for (int k = 0; k < 2; ++k) dst[m][k] = *(const PG8_LAS bf16x8*)(lds + PG8_SA(b, h) + aoff + m * 2048 + k * 1024); } while (0)
; #define PG8_LDB(dst, b, h) do { _Pragma("unroll") for (int n = 0; n < 2; ++n) _Pragma("unroll") for (int k = 0; k < 2; ++k) dst[n][k] = *(const PG8_LAS bf16x8*)(lds + PG8_SB(b, h) + boff + n * 2048 + k * 1024); } while (0)
; #define PG8_MMA(ai, bj, At, Bt) do { __builtin_amdgcn_s_setprio(1); _Pragma("unroll") for (int m = 0; m < 4; ++m) _Pragma("unroll") for (int n = 0; n < 2; ++n) _Pragma("unroll") for (int k = 0; k < 2; ++k) \
;         acc[ai][bj][m][n] = __builtin_amdgcn_mfma_f32_16x16x32_bf16(Bt[n][k], At[m][k], acc[ai][bj][m][n], 0, 0, 0); __builtin_amdgcn_s_setprio(0); } while (0)
; #define PG8_WAIT_V(n) asm volatile("s_waitcnt vmcnt(" #n ")" ::: "memory")
; #define PG8_WAIT_L(n) asm volatile("s_waitcnt lgkmcnt(" #n ")" ::: "memory")
; #define PG8_BAR __builtin_amdgcn_s_barrier()
; #define PG8_SCHED __builtin_amdgcn_sched_barrier(0)
; template <class Epi, class Sched, bool ALIGN_EPI = false, bool SP2 = false>
; __device__ __forceinline__ void gemm_phase(PG8_LAS unsigned char* lds, const Gemm g, const Sched& S, const Epi& E) {
;     ...
;             PG8_LDB(B0, 0, 0); PG8_LDB(B1, 0, 1); PG8_SCHED; PG8_LDA(At, 0, 0); PG8_STAGE(PG8_SA(1, 1), a1 + hstep, voffA);
;             PG8_WAIT_V(8); PG8_WAIT_L(0); PG8_BAR; PG8_MMA(0, 0, At, B0); PG8_MMA(0, 1, At, B1); PG8_BAR; PG8_SCHED;
;             PG8_LDA(At, 0, 1); PG8_STAGE(PG8_SB(0, 0), b2, voffB); PG8_STAGE(PG8_SB(0, 1), b2 + hstep, voffB); PG8_STAGE(PG8_SA(0, 0), a2, voffA);
.LBB0_761:
	s_add_u32 s10, s48, s8
	s_addc_u32 s11, s49, s9
	s_add_u32 s10, s10, 0x1c000100
	s_addc_u32 s11, s11, 0
	s_add_u32 s53, s41, s8
	s_addc_u32 s54, s43, s9
	s_add_i32 s55, 0, 0x10000
	s_cmpk_eq_i32 s8, 0x700
	s_cselect_b32 s13, s7, s11
	s_cselect_b32 s12, s6, s10
	v_add_u32_e32 v142, s55, v136
	s_cselect_b32 s11, s5, s54
	s_cselect_b32 s10, s4, s53
	s_add_i32 s53, 0, 0x14000
	ds_read_b128 v[138:141], v142
	ds_read_b128 v[146:149], v142 offset:1024
	ds_read_b128 v[150:153], v142 offset:2048
	ds_read_b128 v[154:157], v142 offset:3072
	v_add_u32_e32 v142, s53, v136
	ds_read_b128 v[158:161], v142
	ds_read_b128 v[162:165], v142 offset:1024
	ds_read_b128 v[166:169], v142 offset:2048
	ds_read_b128 v[170:173], v142 offset:3072
	v_lshl_add_u64 v[142:143], v[130:131], 0, s[8:9]
	s_add_i32 m0, s37, 0xc000
	ds_read_b128 v[174:177], v137
	ds_read_b128 v[178:181], v137 offset:1024
	ds_read_b128 v[182:185], v137 offset:2048
	ds_read_b128 v[192:195], v137 offset:3072
	ds_read_b128 v[196:199], v137 offset:4096
	ds_read_b128 v[200:203], v137 offset:5120
	ds_read_b128 v[204:207], v137 offset:6144
	ds_read_b128 v[208:211], v137 offset:7168
	global_load_lds_dwordx4 v[142:143], off
	v_lshl_add_u64 v[142:143], v[132:133], 0, s[8:9]
	s_add_i32 m0, s37, 0xe000
	s_nop 0
	global_load_lds_dwordx4 v[142:143], off
	s_waitcnt vmcnt(8)
	s_waitcnt lgkmcnt(0)
	s_barrier
	s_setprio 1
	s_waitcnt lgkmcnt(0)
	v_mfma_f32_16x16x32_bf16 v[124:127], v[138:141], v[174:177], v[124:127]
	v_mfma_f32_16x16x32_bf16 v[120:123], v[150:153], v[174:177], v[120:123]
	v_mfma_f32_16x16x32_bf16 v[116:119], v[138:141], v[182:185], v[116:119]
	v_mfma_f32_16x16x32_bf16 v[112:115], v[150:153], v[182:185], v[112:115]
	v_mfma_f32_16x16x32_bf16 v[108:111], v[138:141], v[196:199], v[108:111]
	v_mfma_f32_16x16x32_bf16 v[100:103], v[150:153], v[196:199], v[100:103]
	v_mfma_f32_16x16x32_bf16 v[92:95], v[138:141], v[204:207], v[92:95]
	v_mfma_f32_16x16x32_bf16 v[84:87], v[150:153], v[204:207], v[84:87]
	v_mfma_f32_16x16x32_bf16 v[124:127], v[146:149], v[178:181], v[124:127]
	v_mfma_f32_16x16x32_bf16 v[120:123], v[154:157], v[178:181], v[120:123]
	v_mfma_f32_16x16x32_bf16 v[116:119], v[146:149], v[192:195], v[116:119]
	v_mfma_f32_16x16x32_bf16 v[112:115], v[154:157], v[192:195], v[112:115]
	v_mfma_f32_16x16x32_bf16 v[108:111], v[146:149], v[200:203], v[108:111]
	v_mfma_f32_16x16x32_bf16 v[100:103], v[154:157], v[200:203], v[100:103]
	v_mfma_f32_16x16x32_bf16 v[92:95], v[146:149], v[208:211], v[92:95]
	v_mfma_f32_16x16x32_bf16 v[84:87], v[154:157], v[208:211], v[84:87]
	s_setprio 0
	s_setprio 1
	v_mfma_f32_16x16x32_bf16 v[104:107], v[158:161], v[174:177], v[104:107]
	v_mfma_f32_16x16x32_bf16 v[96:99], v[166:169], v[174:177], v[96:99]
	v_mfma_f32_16x16x32_bf16 v[88:91], v[158:161], v[182:185], v[88:91]
	v_mfma_f32_16x16x32_bf16 v[80:83], v[166:169], v[182:185], v[80:83]
	v_mfma_f32_16x16x32_bf16 v[76:79], v[158:161], v[196:199], v[76:79]
	v_mfma_f32_16x16x32_bf16 v[72:75], v[166:169], v[196:199], v[72:75]
	v_mfma_f32_16x16x32_bf16 v[68:71], v[158:161], v[204:207], v[68:71]
	v_mfma_f32_16x16x32_bf16 v[64:67], v[166:169], v[204:207], v[64:67]
	v_mfma_f32_16x16x32_bf16 v[104:107], v[162:165], v[178:181], v[104:107]
	v_mfma_f32_16x16x32_bf16 v[96:99], v[170:173], v[178:181], v[96:99]
	v_mfma_f32_16x16x32_bf16 v[88:91], v[162:165], v[192:195], v[88:91]
	v_mfma_f32_16x16x32_bf16 v[80:83], v[170:173], v[192:195], v[80:83]
	v_mfma_f32_16x16x32_bf16 v[76:79], v[162:165], v[200:203], v[76:79]
	v_mfma_f32_16x16x32_bf16 v[72:75], v[170:173], v[200:203], v[72:75]
	v_mfma_f32_16x16x32_bf16 v[68:71], v[162:165], v[208:211], v[68:71]
	v_mfma_f32_16x16x32_bf16 v[64:67], v[170:173], v[208:211], v[64:67]
	s_setprio 0
	s_barrier
	s_add_i32 s54, s55, s36
	v_lshl_add_u64 v[142:143], s[10:11], 0, v[186:187]
	s_mov_b32 m0, s54
	ds_read_b128 v[174:177], v137 offset:16384
	ds_read_b128 v[178:181], v137 offset:17408
	ds_read_b128 v[182:185], v137 offset:18432
	ds_read_b128 v[192:195], v137 offset:19456
	ds_read_b128 v[196:199], v137 offset:20480
	ds_read_b128 v[200:203], v137 offset:21504
	ds_read_b128 v[204:207], v137 offset:22528
	ds_read_b128 v[208:211], v137 offset:23552
	global_load_lds_dwordx4 v[142:143], off
	s_add_i32 m0, s54, 0x2000
	s_add_u32 s54, s10, 0x100000
	v_lshl_add_u64 v[188:189], s[10:11], 0, v[128:129]
	s_addc_u32 s55, s11, 0
	s_add_i32 s53, s53, s36
	global_load_lds_dwordx4 v[188:189], off
	v_lshl_add_u64 v[212:213], s[54:55], 0, v[186:187]
	s_mov_b32 m0, s53
	v_lshl_add_u64 v[214:215], s[12:13], 0, v[128:129]
	global_load_lds_dwordx4 v[212:213], off
	v_lshl_add_u64 v[212:213], s[54:55], 0, v[128:129]
	s_add_i32 m0, s53, 0x2000
	s_nop 0
	global_load_lds_dwordx4 v[212:213], off
	v_lshl_add_u64 v[212:213], s[12:13], 0, v[186:187]
	s_mov_b32 m0, s37
	s_nop 0
	global_load_lds_dwordx4 v[212:213], off
	s_mov_b32 m0, s38
	s_nop 0
	global_load_lds_dwordx4 v[214:215], off
	s_waitcnt vmcnt(8)
	s_waitcnt lgkmcnt(0)
	s_barrier
; #define PG8_STAGE(bufoff, gbase, voff) do { _Pragma("unroll") for (int _i = 0; _i < 2; ++_i) \
;         __builtin_amdgcn_global_load_lds((const unsigned*)((const char*)(gbase) + (voff)[_i]), (PG8_LAS unsigned*)(lds + (bufoff) + ldsw + _i * 8192), 16, 0, 0); } while (0)
; #define PG8_LDA(dst, b, h) do { _Pragma("unroll") for (int m = 0; m < 4; ++m) _Pragma("unroll") for (int k = 0; k < 2; ++k) dst[m][k] = *(const PG8_LAS bf16x8*)(lds + PG8_SA(b, h) + aoff + m * 2048 + k * 1024); } while (0)
; #define PG8_LDB(dst, b, h) do { _Pragma("unroll") for (int n = 0; n < 2; ++n) _Pragma("unroll") for (int k = 0; k < 2; ++k) dst[n][k] = *(const PG8_LAS bf16x8*)(lds + PG8_SB(b, h) + boff + n * 2048 + k * 1024); } while (0)
; #define PG8_MMA(ai, bj, At, Bt) do { __builtin_amdgcn_s_setprio(1); _Pragma("unroll") for (int m = 0; m < 4; ++m) _Pragma("unroll") for (int n = 0; n < 2; ++n) _Pragma("unroll") for (int k = 0; k < 2; ++k) \
;         acc[ai][bj][m][n] = __builtin_amdgcn_mfma_f32_16x16x32_bf16(Bt[n][k], At[m][k], acc[ai][bj][m][n], 0, 0, 0); __builtin_amdgcn_s_setprio(0); } while (0)
; #define PG8_WAIT_V(n) asm volatile("s_waitcnt vmcnt(" #n ")" ::: "memory")
; #define PG8_WAIT_L(n) asm volatile("s_waitcnt lgkmcnt(" #n ")" ::: "memory")
; #define PG8_BAR __builtin_amdgcn_s_barrier()
; #define PG8_SCHED __builtin_amdgcn_sched_barrier(0)
; template <class Epi, class Sched, bool ALIGN_EPI = false, bool SP2 = false>
; __device__ __forceinline__ void gemm_phase(PG8_LAS unsigned char* lds, const Gemm g, const Sched& S, const Epi& E) {
;     ...
;             PG8_WAIT_V(8); PG8_WAIT_L(0); PG8_BAR; PG8_MMA(1, 0, At, B0); PG8_MMA(1, 1, At, B1); PG8_BAR; PG8_SCHED;
;             PG8_LDB(B0, 1, 0); PG8_LDB(B1, 1, 1); PG8_SCHED; PG8_LDA(At, 1, 0); PG8_STAGE(PG8_SA(0, 1), a2 + hstep, voffA);
;             PG8_WAIT_V(8); PG8_WAIT_L(0); PG8_BAR; PG8_MMA(0, 0, At, B0); PG8_MMA(0, 1, At, B1); PG8_BAR; PG8_SCHED;
	s_setprio 1
	s_waitcnt lgkmcnt(0)
	v_mfma_f32_16x16x32_bf16 v[60:63], v[138:141], v[174:177], v[60:63]
	v_mfma_f32_16x16x32_bf16 v[56:59], v[150:153], v[174:177], v[56:59]
	v_mfma_f32_16x16x32_bf16 v[52:55], v[138:141], v[182:185], v[52:55]
	v_mfma_f32_16x16x32_bf16 v[48:51], v[150:153], v[182:185], v[48:51]
	v_mfma_f32_16x16x32_bf16 v[44:47], v[138:141], v[196:199], v[44:47]
	v_mfma_f32_16x16x32_bf16 v[40:43], v[150:153], v[196:199], v[40:43]
	v_mfma_f32_16x16x32_bf16 v[32:35], v[138:141], v[204:207], v[32:35]
	v_mfma_f32_16x16x32_bf16 v[24:27], v[150:153], v[204:207], v[24:27]
	v_mfma_f32_16x16x32_bf16 v[60:63], v[146:149], v[178:181], v[60:63]
	v_mfma_f32_16x16x32_bf16 v[56:59], v[154:157], v[178:181], v[56:59]
	v_mfma_f32_16x16x32_bf16 v[52:55], v[146:149], v[192:195], v[52:55]
	v_mfma_f32_16x16x32_bf16 v[48:51], v[154:157], v[192:195], v[48:51]
	v_mfma_f32_16x16x32_bf16 v[44:47], v[146:149], v[200:203], v[44:47]
	v_mfma_f32_16x16x32_bf16 v[40:43], v[154:157], v[200:203], v[40:43]
	v_mfma_f32_16x16x32_bf16 v[32:35], v[146:149], v[208:211], v[32:35]
	v_mfma_f32_16x16x32_bf16 v[24:27], v[154:157], v[208:211], v[24:27]
	s_setprio 0
	s_setprio 1
	v_mfma_f32_16x16x32_bf16 v[36:39], v[158:161], v[174:177], v[36:39]
	v_mfma_f32_16x16x32_bf16 v[28:31], v[166:169], v[174:177], v[28:31]
	v_mfma_f32_16x16x32_bf16 v[20:23], v[158:161], v[182:185], v[20:23]
	v_mfma_f32_16x16x32_bf16 v[16:19], v[166:169], v[182:185], v[16:19]
	v_mfma_f32_16x16x32_bf16 v[12:15], v[158:161], v[196:199], v[12:15]
	v_mfma_f32_16x16x32_bf16 v[8:11], v[166:169], v[196:199], v[8:11]
	v_mfma_f32_16x16x32_bf16 v[4:7], v[158:161], v[204:207], v[4:7]
	v_mfma_f32_16x16x32_bf16 v[0:3], v[166:169], v[204:207], v[0:3]
	v_mfma_f32_16x16x32_bf16 v[36:39], v[162:165], v[178:181], v[36:39]
	v_mfma_f32_16x16x32_bf16 v[28:31], v[170:173], v[178:181], v[28:31]
	v_mfma_f32_16x16x32_bf16 v[20:23], v[162:165], v[192:195], v[20:23]
	v_mfma_f32_16x16x32_bf16 v[16:19], v[170:173], v[192:195], v[16:19]
	v_mfma_f32_16x16x32_bf16 v[12:15], v[162:165], v[200:203], v[12:15]
	v_mfma_f32_16x16x32_bf16 v[8:11], v[170:173], v[200:203], v[8:11]
	v_mfma_f32_16x16x32_bf16 v[4:7], v[162:165], v[208:211], v[4:7]
	v_mfma_f32_16x16x32_bf16 v[0:3], v[170:173], v[208:211], v[0:3]
	s_setprio 0
	s_barrier
	s_add_i32 s53, 0, 0x18000
	v_add_u32_e32 v145, s53, v136
	s_add_i32 s54, 0, 0x1c000
	ds_read_b128 v[138:141], v145
	ds_read_b128 v[146:149], v145 offset:1024
	ds_read_b128 v[150:153], v145 offset:2048
	ds_read_b128 v[154:157], v145 offset:3072
	v_add_u32_e32 v145, s54, v136
	ds_read_b128 v[158:161], v145
	ds_read_b128 v[162:165], v145 offset:1024
	ds_read_b128 v[166:169], v145 offset:2048
	ds_read_b128 v[170:173], v145 offset:3072
	s_add_u32 s12, s12, 0x100000
	s_addc_u32 s13, s13, 0
	s_mov_b32 m0, s39
	v_lshl_add_u64 v[216:217], s[12:13], 0, v[186:187]
	ds_read_b128 v[174:177], v137 offset:32768
	ds_read_b128 v[178:181], v137 offset:33792
	ds_read_b128 v[182:185], v137 offset:34816
	ds_read_b128 v[192:195], v137 offset:35840
	ds_read_b128 v[196:199], v137 offset:36864
	ds_read_b128 v[200:203], v137 offset:37888
	ds_read_b128 v[204:207], v137 offset:38912
	ds_read_b128 v[208:211], v137 offset:39936
	global_load_lds_dwordx4 v[216:217], off
	v_lshl_add_u64 v[216:217], s[12:13], 0, v[128:129]
	s_mov_b32 m0, s40
	s_nop 0
	global_load_lds_dwordx4 v[216:217], off
	s_waitcnt vmcnt(8)
	s_waitcnt lgkmcnt(0)
	s_barrier
	s_setprio 1
	s_waitcnt lgkmcnt(0)
	v_mfma_f32_16x16x32_bf16 v[124:127], v[138:141], v[174:177], v[124:127]
	v_mfma_f32_16x16x32_bf16 v[120:123], v[150:153], v[174:177], v[120:123]
	v_mfma_f32_16x16x32_bf16 v[116:119], v[138:141], v[182:185], v[116:119]
	v_mfma_f32_16x16x32_bf16 v[112:115], v[150:153], v[182:185], v[112:115]
	v_mfma_f32_16x16x32_bf16 v[108:111], v[138:141], v[196:199], v[108:111]
	v_mfma_f32_16x16x32_bf16 v[100:103], v[150:153], v[196:199], v[100:103]
	v_mfma_f32_16x16x32_bf16 v[92:95], v[138:141], v[204:207], v[92:95]
	v_mfma_f32_16x16x32_bf16 v[84:87], v[150:153], v[204:207], v[84:87]
	v_mfma_f32_16x16x32_bf16 v[124:127], v[146:149], v[178:181], v[124:127]
	v_mfma_f32_16x16x32_bf16 v[120:123], v[154:157], v[178:181], v[120:123]
	v_mfma_f32_16x16x32_bf16 v[116:119], v[146:149], v[192:195], v[116:119]
	v_mfma_f32_16x16x32_bf16 v[112:115], v[154:157], v[192:195], v[112:115]
	v_mfma_f32_16x16x32_bf16 v[108:111], v[146:149], v[200:203], v[108:111]
	v_mfma_f32_16x16x32_bf16 v[100:103], v[154:157], v[200:203], v[100:103]
	v_mfma_f32_16x16x32_bf16 v[92:95], v[146:149], v[208:211], v[92:95]
	v_mfma_f32_16x16x32_bf16 v[84:87], v[154:157], v[208:211], v[84:87]
	s_setprio 0
	s_setprio 1
	v_mfma_f32_16x16x32_bf16 v[104:107], v[158:161], v[174:177], v[104:107]
	v_mfma_f32_16x16x32_bf16 v[96:99], v[166:169], v[174:177], v[96:99]
	v_mfma_f32_16x16x32_bf16 v[88:91], v[158:161], v[182:185], v[88:91]
	v_mfma_f32_16x16x32_bf16 v[80:83], v[166:169], v[182:185], v[80:83]
	v_mfma_f32_16x16x32_bf16 v[76:79], v[158:161], v[196:199], v[76:79]
	v_mfma_f32_16x16x32_bf16 v[72:75], v[166:169], v[196:199], v[72:75]
	v_mfma_f32_16x16x32_bf16 v[68:71], v[158:161], v[204:207], v[68:71]
	v_mfma_f32_16x16x32_bf16 v[64:67], v[166:169], v[204:207], v[64:67]
	v_mfma_f32_16x16x32_bf16 v[104:107], v[162:165], v[178:181], v[104:107]
	v_mfma_f32_16x16x32_bf16 v[96:99], v[170:173], v[178:181], v[96:99]
	v_mfma_f32_16x16x32_bf16 v[88:91], v[162:165], v[192:195], v[88:91]
	v_mfma_f32_16x16x32_bf16 v[80:83], v[170:173], v[192:195], v[80:83]
	v_mfma_f32_16x16x32_bf16 v[76:79], v[162:165], v[200:203], v[76:79]
	v_mfma_f32_16x16x32_bf16 v[72:75], v[170:173], v[200:203], v[72:75]
	v_mfma_f32_16x16x32_bf16 v[68:71], v[162:165], v[208:211], v[68:71]
	v_mfma_f32_16x16x32_bf16 v[64:67], v[170:173], v[208:211], v[64:67]
	s_setprio 0
	s_barrier
; #define PG8_STAGE(bufoff, gbase, voff) do { _Pragma("unroll") for (int _i = 0; _i < 2; ++_i) \
;         __builtin_amdgcn_global_load_lds((const unsigned*)((const char*)(gbase) + (voff)[_i]), (PG8_LAS unsigned*)(lds + (bufoff) + ldsw + _i * 8192), 16, 0, 0); } while (0)
; #define PG8_LDA(dst, b, h) do { _Pragma("unroll") for (int m = 0; m < 4; ++m) _Pragma("unroll") for (int k = 0; k < 2; ++k) dst[m][k] = *(const PG8_LAS bf16x8*)(lds + PG8_SA(b, h) + aoff + m * 2048 + k * 1024); } while (0)
; #define PG8_MMA(ai, bj, At, Bt) do { __builtin_amdgcn_s_setprio(1); _Pragma("unroll") for (int m = 0; m < 4; ++m) _Pragma("unroll") for (int n = 0; n < 2; ++n) _Pragma("unroll") for (int k = 0; k < 2; ++k) \
;         acc[ai][bj][m][n] = __builtin_amdgcn_mfma_f32_16x16x32_bf16(Bt[n][k], At[m][k], acc[ai][bj][m][n], 0, 0, 0); __builtin_amdgcn_s_setprio(0); } while (0)
; #define PG8_WAIT_V(n) asm volatile("s_waitcnt vmcnt(" #n ")" ::: "memory")
; #define PG8_WAIT_L(n) asm volatile("s_waitcnt lgkmcnt(" #n ")" ::: "memory")
; #define PG8_BAR __builtin_amdgcn_s_barrier()
; #define PG8_SCHED __builtin_amdgcn_sched_barrier(0)
; template <class Epi, class Sched, bool ALIGN_EPI = false, bool SP2 = false>
; __device__ __forceinline__ void gemm_phase(PG8_LAS unsigned char* lds, const Gemm g, const Sched& S, const Epi& E) {
;     ...
;             PG8_LDA(At, 1, 1); PG8_STAGE(PG8_SB(1, 0), b3, voffB); PG8_STAGE(PG8_SB(1, 1), b3 + hstep, voffB); PG8_STAGE(PG8_SA(1, 0), a3, voffA);
;             PG8_WAIT_V(8); PG8_WAIT_L(0); PG8_BAR; PG8_MMA(1, 0, At, B0); PG8_MMA(1, 1, At, B1); PG8_BAR; PG8_SCHED;
	s_add_i32 s12, s53, s36
	v_lshl_add_u64 v[142:143], v[142:143], 0, s[44:45]
	s_mov_b32 m0, s12
	ds_read_b128 v[174:177], v137 offset:49152
	ds_read_b128 v[178:181], v137 offset:50176
	ds_read_b128 v[182:185], v137 offset:51200
	ds_read_b128 v[192:195], v137 offset:52224
	ds_read_b128 v[196:199], v137 offset:53248
	ds_read_b128 v[200:203], v137 offset:54272
	ds_read_b128 v[204:207], v137 offset:55296
	ds_read_b128 v[208:211], v137 offset:56320
	global_load_lds_dwordx4 v[142:143], off
	s_add_i32 m0, s12, 0x2000
	s_add_u32 s10, s10, 0x100080
	v_lshl_add_u64 v[142:143], v[188:189], 0, s[44:45]
	s_addc_u32 s11, s11, 0
	s_add_i32 s12, s54, s36
	global_load_lds_dwordx4 v[142:143], off
	v_lshl_add_u64 v[142:143], s[10:11], 0, v[186:187]
	s_mov_b32 m0, s12
	s_nop 0
	global_load_lds_dwordx4 v[142:143], off
	v_lshl_add_u64 v[142:143], s[10:11], 0, v[128:129]
	s_add_i32 m0, s12, 0x2000
	s_nop 0
	global_load_lds_dwordx4 v[142:143], off
	v_lshl_add_u64 v[142:143], v[212:213], 0, s[44:45]
	s_mov_b32 m0, s46
	s_nop 0
	global_load_lds_dwordx4 v[142:143], off
	v_lshl_add_u64 v[142:143], v[214:215], 0, s[44:45]
	s_mov_b32 m0, s47
	s_nop 0
	global_load_lds_dwordx4 v[142:143], off
	s_waitcnt vmcnt(8)
	s_waitcnt lgkmcnt(0)
	s_barrier
	s_setprio 1
	s_waitcnt lgkmcnt(0)
	v_mfma_f32_16x16x32_bf16 v[60:63], v[138:141], v[174:177], v[60:63]
	v_mfma_f32_16x16x32_bf16 v[56:59], v[150:153], v[174:177], v[56:59]
	v_mfma_f32_16x16x32_bf16 v[52:55], v[138:141], v[182:185], v[52:55]
	v_mfma_f32_16x16x32_bf16 v[48:51], v[150:153], v[182:185], v[48:51]
	v_mfma_f32_16x16x32_bf16 v[44:47], v[138:141], v[196:199], v[44:47]
	v_mfma_f32_16x16x32_bf16 v[40:43], v[150:153], v[196:199], v[40:43]
	v_mfma_f32_16x16x32_bf16 v[32:35], v[138:141], v[204:207], v[32:35]
	v_mfma_f32_16x16x32_bf16 v[24:27], v[150:153], v[204:207], v[24:27]
	v_mfma_f32_16x16x32_bf16 v[60:63], v[146:149], v[178:181], v[60:63]
	v_mfma_f32_16x16x32_bf16 v[56:59], v[154:157], v[178:181], v[56:59]
	v_mfma_f32_16x16x32_bf16 v[52:55], v[146:149], v[192:195], v[52:55]
	v_mfma_f32_16x16x32_bf16 v[48:51], v[154:157], v[192:195], v[48:51]
	v_mfma_f32_16x16x32_bf16 v[44:47], v[146:149], v[200:203], v[44:47]
	v_mfma_f32_16x16x32_bf16 v[40:43], v[154:157], v[200:203], v[40:43]
	v_mfma_f32_16x16x32_bf16 v[32:35], v[146:149], v[208:211], v[32:35]
	v_mfma_f32_16x16x32_bf16 v[24:27], v[154:157], v[208:211], v[24:27]
	s_setprio 0
	s_setprio 1
	v_mfma_f32_16x16x32_bf16 v[36:39], v[158:161], v[174:177], v[36:39]
	v_mfma_f32_16x16x32_bf16 v[28:31], v[166:169], v[174:177], v[28:31]
	v_mfma_f32_16x16x32_bf16 v[20:23], v[158:161], v[182:185], v[20:23]
	v_mfma_f32_16x16x32_bf16 v[16:19], v[166:169], v[182:185], v[16:19]
	v_mfma_f32_16x16x32_bf16 v[12:15], v[158:161], v[196:199], v[12:15]
	v_mfma_f32_16x16x32_bf16 v[8:11], v[166:169], v[196:199], v[8:11]
	v_mfma_f32_16x16x32_bf16 v[4:7], v[158:161], v[204:207], v[4:7]
	v_mfma_f32_16x16x32_bf16 v[0:3], v[166:169], v[204:207], v[0:3]
	v_mfma_f32_16x16x32_bf16 v[36:39], v[162:165], v[178:181], v[36:39]
	v_mfma_f32_16x16x32_bf16 v[28:31], v[170:173], v[178:181], v[28:31]
	v_mfma_f32_16x16x32_bf16 v[20:23], v[162:165], v[192:195], v[20:23]
	v_mfma_f32_16x16x32_bf16 v[16:19], v[170:173], v[192:195], v[16:19]
	v_mfma_f32_16x16x32_bf16 v[12:15], v[162:165], v[200:203], v[12:15]
	v_mfma_f32_16x16x32_bf16 v[8:11], v[170:173], v[200:203], v[8:11]
	v_mfma_f32_16x16x32_bf16 v[4:7], v[162:165], v[208:211], v[4:7]
	v_mfma_f32_16x16x32_bf16 v[0:3], v[170:173], v[208:211], v[0:3]
	s_setprio 0
	s_barrier
	s_add_i32 s52, s52, 2
	s_add_u32 s8, s8, 0x100
	s_addc_u32 s9, s9, 0
	s_cmp_gt_u32 s52, 13
	s_cbranch_scc0 .LBB0_761
	s_cmpk_lt_u32 s35, 0x100
	s_movk_i32 s46, 0x4000
	s_cbranch_scc0 .LBB0_757
	s_barrier
	s_branch .LBB0_757
